# v22 + XCD-local grid barrier (no L2 writeback, no cross-XCD hop) after the out-projection GEMM and after MLP1, guarded by a runtime workgroup-placement check
# speedup vs baseline: 1.0025x; 1.0025x over previous
; #define LAS __attribute__((address_space(3)))
; __device__ __forceinline__ unsigned xb_add(unsigned* p, unsigned v) { return __hip_atomic_fetch_add(p, v, __ATOMIC_RELAXED, __HIP_MEMORY_SCOPE_AGENT); }
; __device__ __forceinline__ unsigned xb_xcc_id() { return (unsigned)__builtin_amdgcn_s_getreg((3 << 11) | 20) & 0xFu; }
; __device__ __forceinline__ XcdBarrier xcd_barrier_post(unsigned* bar, volatile LAS unsigned* st) {
;     XcdBarrier b; b.bar = bar; b.x = xb_xcc_id(); b.st = st;
;     if (threadIdx.x == 0) (void)xb_add(&bar[XB_XCNT(b.x)], 1u);
;     return b;
; }
; __global__ void __launch_bounds__(NTHR, 2) fwd_megakernel(Args a) {
;     extern __shared__ __attribute__((aligned(16))) unsigned char lds_raw[];
;     cg::grid_group grid = cg::this_grid();
;     LAS unsigned char* lds = (LAS unsigned char*)lds_raw;
;     const int tid = threadIdx.x, lane = tid & 63, wave = __builtin_amdgcn_readfirstlane(tid >> 6);
;     const int G = gridDim.x, gw = blockIdx.x * NWAVES + wave, NGW = G * NWAVES;
;     unsigned char* ws = a.ws;
;     float* ssq = (float*)(ws + WS_SSQ); float* lse = (float*)(ws + WS_WIN);
;     bf16* Win_t = (bf16*)(ws + WS_WIN); bf16* Wout_t = (bf16*)(ws + WS_WOUT); bf16* Wqkv_t = (bf16*)(ws + WS_WQKV); bf16* Waout_t = (bf16*)(ws + WS_WAOUT);
;     bf16* W1_t = (bf16*)(ws + WS_W1); bf16* W2_t = (bf16*)(ws + WS_W2);
;     bf16* XB = (bf16*)(ws + WS_XB); bf16* OB = (bf16*)(ws + WS_OB); bf16* BIG = (bf16*)(ws + WS_BIG);
;     float* xres = a.out;
;     volatile LAS unsigned* MISC = (volatile LAS unsigned*)(lds + 146944);
;     if (tid < 32) MISC[tid] = 0u;
;     __syncthreads();
;     XcdBarrier bar = xcd_barrier_post((unsigned*)(ws + WS_CTL), MISC + 8);
_Z14fwd_megakernel4Args:
	s_load_dword s34, s[0:1], 0x78
	s_load_dwordx4 s[16:19], s[0:1], 0x60
	s_load_dwordx8 s[4:11], s[0:1], 0x40
	s_load_dwordx2 s[66:67], s[0:1], 0x70
	s_add_u32 s12, s0, 0x70
	v_and_b32_e32 v163, 0x3ff, v0
	s_waitcnt lgkmcnt(0)
	v_writelane_b32 v251, s16, 0
	s_mov_b32 s78, s2
	s_addc_u32 s13, s1, 0
	v_writelane_b32 v251, s17, 1
	v_writelane_b32 v251, s18, 2
	v_readfirstlane_b32 s2, v163
	v_cmp_gt_u32_e32 vcc, 32, v163
	v_writelane_b32 v251, s19, 3
	s_and_saveexec_b64 s[14:15], vcc
	v_lshl_add_u32 v1, v163, 2, 0
	v_add_u32_e32 v1, 0x23e00, v1
	v_mov_b32_e32 v2, 0
	ds_write_b32 v1, v2
	s_or_b64 exec, exec, s[14:15]
	s_load_dwordx16 s[16:31], s[0:1], 0x0
	s_waitcnt lgkmcnt(0)
	s_barrier
	s_getreg_b32 s33, hwreg(HW_REG_XCC_ID, 0, 4)
	v_writelane_b32 v251, s16, 4
	s_nop 1
	v_writelane_b32 v251, s17, 5
	v_writelane_b32 v251, s18, 6
	v_writelane_b32 v251, s19, 7
	v_writelane_b32 v251, s20, 8
	v_writelane_b32 v251, s21, 9
	v_writelane_b32 v251, s22, 10
	v_writelane_b32 v251, s23, 11
	v_writelane_b32 v251, s24, 12
	v_writelane_b32 v251, s25, 13
	v_writelane_b32 v251, s26, 14
	v_writelane_b32 v251, s27, 15
	v_writelane_b32 v251, s28, 16
	v_writelane_b32 v251, s29, 17
	v_writelane_b32 v251, s30, 18
	v_writelane_b32 v251, s31, 19
	s_nop 0
	v_readlane_b32 s16, v251, 0
	v_readlane_b32 s18, v251, 2
	v_readlane_b32 s19, v251, 3
	s_add_u32 s0, s18, 0x200000
	s_addc_u32 s1, s19, 0
	v_readlane_b32 s17, v251, 1
	v_writelane_b32 v251, s0, 20
	s_and_b32 s3, s33, 15
	v_cmp_eq_u32_e64 s[16:17], 0, v163
	v_writelane_b32 v251, s1, 21
	s_mov_b32 s1, 0
	s_mov_b64 s[14:15], exec
	v_writelane_b32 v251, s16, 22
	s_nop 1
	v_writelane_b32 v251, s17, 23
	s_and_b64 s[16:17], s[14:15], s[16:17]
	s_mov_b64 exec, s[16:17]
	s_cbranch_execz .LBB0_5
	s_mov_b64 s[16:17], exec
	v_mbcnt_lo_u32_b32 v1, s16, 0
	v_mbcnt_hi_u32_b32 v1, s17, v1
	v_cmp_eq_u32_e32 vcc, 0, v1
	s_and_b64 s[18:19], exec, vcc
	s_mov_b64 exec, s[18:19]
	s_cbranch_execz .LBB0_5
	s_bcnt1_i32_b64 s16, s[16:17]
	s_lshl_b32 s0, s3, 8
	v_mov_b32_e32 v2, s16
	v_readlane_b32 s16, v251, 20
	v_mov_b32_e32 v1, s0
	v_readlane_b32 s17, v251, 21
	s_nop 4
	global_atomic_add v1, v2, s[16:17] offset:1024
	s_and_b32 s0, s78, 7
	s_lshl_b32 s0, s0, 8
	s_addk_i32 s0, 0x4000
	v_mov_b32_e32 v1, s0
	s_lshl_b32 s0, 1, s3
	v_mov_b32_e32 v2, s0
	global_atomic_or v1, v2, s[16:17]

; __device__ __forceinline__ unsigned xb_ld(unsigned* p)              { return __hip_atomic_load(p, __ATOMIC_RELAXED, __HIP_MEMORY_SCOPE_AGENT); }
; __device__ __forceinline__ void xcd_barrier_complete(unsigned* bar, unsigned x, unsigned& nloc, unsigned& nx) {
;     const unsigned G = gridDim.x * gridDim.y * gridDim.z;
;     unsigned sum, cnt, mine, sp = 0u;
;     for (;;) {
;         sum = 0u; cnt = 0u; mine = 0u;
; #pragma unroll
;         for (unsigned j = 0; j < 16; ++j) { const unsigned c = xb_ld(&bar[XB_XCNT(j)]); sum += c; cnt += (c > 0u) ? 1u : 0u; mine = (j == x) ? c : mine; }
;         if (sum == G) break;
;         __builtin_amdgcn_s_sleep(1);
;         if ((++sp & 255u) == 0u) { if (xb_ld(&bar[XB_TMO])) break; if (sp > XB_SPIN_CAP) { atomicAdd(&bar[XB_TMO], 1u); break; } }
;     }
;     nloc = mine > 0u ? mine : 1u; nx = cnt > 0u ? cnt : 1u;
; }
; __device__ __forceinline__ void xcd_barrier(const XcdBarrier& b) {
;     ...
;         if (nloc == 0u) { xcd_barrier_complete(bar, b.x, nloc, nx); b.st[0] = nloc; b.st[1] = nx; }
.LBB0_274:
	s_or_b64 exec, exec, s[6:7]
	v_readlane_b32 s6, v250, 6
	v_readlane_b32 s7, v250, 7
	v_cmp_ne_u32_e32 vcc, 0, v12
	v_readlane_b32 s2, v250, 16
	v_cndmask_b32_e64 v17, 0, v12, s[6:7]
	v_readlane_b32 s6, v250, 4
	v_readlane_b32 s7, v250, 5
	v_cndmask_b32_e64 v12, 0, 1, vcc
	v_cmp_ne_u32_e32 vcc, 0, v0
	v_cndmask_b32_e64 v17, v17, v0, s[6:7]
	v_readlane_b32 s6, v250, 2
	v_readlane_b32 s7, v250, 3
	v_addc_co_u32_e32 v0, vcc, 0, v12, vcc
	s_nop 0
	v_cndmask_b32_e64 v17, v17, v2, s[6:7]
	v_readlane_b32 s6, v250, 0
	v_readlane_b32 s7, v250, 1
	v_cmp_ne_u32_e32 vcc, 0, v2
	s_nop 0
	v_cndmask_b32_e64 v17, v17, v3, s[6:7]
	v_readlane_b32 s6, v251, 62
	v_readlane_b32 s7, v251, 63
	v_cndmask_b32_e64 v2, 0, 1, vcc
	v_cmp_ne_u32_e32 vcc, 0, v3
	v_cndmask_b32_e64 v17, v17, v4, s[6:7]
	v_readlane_b32 s6, v251, 60
	v_readlane_b32 s7, v251, 61
	v_addc_co_u32_e32 v0, vcc, v0, v2, vcc
	s_nop 0
	v_cndmask_b32_e64 v17, v17, v5, s[6:7]
	v_readlane_b32 s6, v251, 58
	v_readlane_b32 s7, v251, 59
	v_cmp_ne_u32_e32 vcc, 0, v4
	v_mov_b32_e32 v3, s2
	v_cndmask_b32_e64 v17, v17, v6, s[6:7]
	v_readlane_b32 s6, v251, 56
	v_readlane_b32 s7, v251, 57
	v_cndmask_b32_e64 v2, 0, 1, vcc
	v_cmp_ne_u32_e32 vcc, 0, v5
	v_cndmask_b32_e64 v17, v17, v7, s[6:7]
	v_readlane_b32 s6, v251, 54
	v_readlane_b32 s7, v251, 55
	v_addc_co_u32_e32 v0, vcc, v0, v2, vcc
	s_nop 0
	v_cndmask_b32_e64 v17, v17, v8, s[6:7]
	v_readlane_b32 s6, v251, 52
	v_readlane_b32 s7, v251, 53
	v_cmp_ne_u32_e32 vcc, 0, v6
	v_readlane_b32 s2, v250, 17
	v_cndmask_b32_e64 v17, v17, v9, s[6:7]
	v_readlane_b32 s6, v251, 50
	v_cndmask_b32_e64 v2, 0, 1, vcc
	v_cmp_ne_u32_e32 vcc, 0, v7
	v_readlane_b32 s7, v251, 51
	s_nop 0
	v_addc_co_u32_e32 v0, vcc, v0, v2, vcc
	v_cndmask_b32_e64 v17, v17, v10, s[6:7]
	v_readlane_b32 s6, v251, 48
	v_cmp_ne_u32_e32 vcc, 0, v8
	v_readlane_b32 s7, v251, 49
	s_nop 0
	v_cndmask_b32_e64 v2, 0, 1, vcc
	v_cmp_ne_u32_e32 vcc, 0, v9
	v_cndmask_b32_e64 v17, v17, v11, s[6:7]
	v_readlane_b32 s6, v251, 46
	v_addc_co_u32_e32 v0, vcc, v0, v2, vcc
	v_readlane_b32 s7, v251, 47
	v_cmp_ne_u32_e32 vcc, 0, v10
	s_nop 0
	v_cndmask_b32_e64 v17, v17, v13, s[6:7]
	v_readlane_b32 s6, v251, 44
	v_cndmask_b32_e64 v2, 0, 1, vcc
	v_cmp_ne_u32_e32 vcc, 0, v11
	v_readlane_b32 s7, v251, 45
	s_nop 0
	v_addc_co_u32_e32 v0, vcc, v0, v2, vcc
	v_cndmask_b32_e64 v17, v17, v14, s[6:7]
	v_readlane_b32 s6, v251, 42
	v_cmp_ne_u32_e32 vcc, 0, v13
	v_readlane_b32 s7, v251, 43
	s_nop 0
	v_cndmask_b32_e64 v2, 0, 1, vcc
	v_cmp_ne_u32_e32 vcc, 0, v14
	v_cndmask_b32_e64 v17, v17, v15, s[6:7]
	v_readlane_b32 s6, v251, 40
	v_addc_co_u32_e32 v0, vcc, v0, v2, vcc
	v_readlane_b32 s7, v251, 41
	v_cmp_ne_u32_e32 vcc, 0, v15
	s_nop 0
	v_cndmask_b32_e64 v17, v17, v16, s[6:7]
	v_cndmask_b32_e64 v2, 0, 1, vcc
	v_cmp_ne_u32_e32 vcc, 0, v16
	s_nop 1
	v_addc_co_u32_e32 v0, vcc, v0, v2, vcc
	v_max_u32_e32 v2, 1, v17
	v_max_u32_e32 v0, 1, v0
	ds_write_b32 v3, v2
	v_mov_b32_e32 v3, s2
	ds_write_b32 v3, v0
	s_add_u32 s6, s4, 0x4000
	s_addc_u32 s7, s5, 0
	v_mov_b32_e32 v4, 0
	global_load_dword v5, v4, s[6:7] sc1
	global_load_dword v6, v4, s[6:7] offset:256 sc1
	global_load_dword v7, v4, s[6:7] offset:512 sc1
	global_load_dword v8, v4, s[6:7] offset:768 sc1
	global_load_dword v9, v4, s[6:7] offset:1024 sc1
	global_load_dword v10, v4, s[6:7] offset:1280 sc1
	global_load_dword v11, v4, s[6:7] offset:1536 sc1
	global_load_dword v12, v4, s[6:7] offset:1792 sc1
	s_waitcnt vmcnt(0)
	v_mov_b32_e32 v13, 0
	v_bcnt_u32_b32 v14, v5, 0
	v_add_u32_e32 v14, -1, v14
	v_or_b32_e32 v13, v13, v14
	v_bcnt_u32_b32 v14, v6, 0
	v_add_u32_e32 v14, -1, v14
	v_or_b32_e32 v13, v13, v14
	v_bcnt_u32_b32 v14, v7, 0
	v_add_u32_e32 v14, -1, v14
	v_or_b32_e32 v13, v13, v14
	v_bcnt_u32_b32 v14, v8, 0
	v_add_u32_e32 v14, -1, v14
	v_or_b32_e32 v13, v13, v14
	v_bcnt_u32_b32 v14, v9, 0
	v_add_u32_e32 v14, -1, v14
	v_or_b32_e32 v13, v13, v14
	v_bcnt_u32_b32 v14, v10, 0
	v_add_u32_e32 v14, -1, v14
	v_or_b32_e32 v13, v13, v14
	v_bcnt_u32_b32 v14, v11, 0
	v_add_u32_e32 v14, -1, v14
	v_or_b32_e32 v13, v13, v14
	v_bcnt_u32_b32 v14, v12, 0
	v_add_u32_e32 v14, -1, v14
	v_or_b32_e32 v13, v13, v14
	v_cmp_eq_u32_e32 vcc, 0, v13
	s_nop 1
	v_cndmask_b32_e64 v13, 0, 1, vcc
	v_mov_b32_e32 v3, 0x23e28
	ds_write_b32 v3, v13

; __device__ __forceinline__ unsigned xb_ld(unsigned* p)              { return __hip_atomic_load(p, __ATOMIC_RELAXED, __HIP_MEMORY_SCOPE_AGENT); }
; __device__ __forceinline__ unsigned xb_add(unsigned* p, unsigned v) { return __hip_atomic_fetch_add(p, v, __ATOMIC_RELAXED, __HIP_MEMORY_SCOPE_AGENT); }
; #define XB_SPIN(cond, bar) do { unsigned _sp = 0; while (cond) { __builtin_amdgcn_s_sleep(1); \
;     if ((++_sp & 255u) == 0u) { if (xb_ld(&(bar)[XB_TMO])) break; if (_sp > XB_SPIN_CAP) { atomicAdd(&(bar)[XB_TMO], 1u); break; } } } } while (0)
; __device__ __forceinline__ void xcd_barrier(const XcdBarrier& b) {
;     ...
;         if (nloc == 0u) { xcd_barrier_complete(bar, b.x, nloc, nx); b.st[0] = nloc; b.st[1] = nx; }
;         const unsigned old = xb_add(&bar[XB_XSUB(b.x)], 1u);
;         const unsigned gen = old / nloc;
;         if (old + 1u == (gen + 1u) * nloc) {
;             __builtin_amdgcn_fence(__ATOMIC_RELEASE, "agent");
;             asm volatile("s_waitcnt vmcnt(0)" ::: "memory");
;             const unsigned og = xb_add(&bar[XB_TOP], 1u);
;             const unsigned tg = og / nx;
;             if (og + 1u == (tg + 1u) * nx) xb_add(&bar[XB_TOPGEN], 1u);
;             else XB_SPIN(xb_ld(&bar[XB_TOPGEN]) == tg, bar);
;             __builtin_amdgcn_fence(__ATOMIC_ACQUIRE, "agent");
;             xb_add(&bar[XB_XGEN(b.x)], 1u);
;             asm volatile("s_waitcnt vmcnt(0)" ::: "memory");
;         } else {
;             XB_SPIN(xb_ld(&bar[XB_XGEN(b.x)]) == gen, bar);
;             __builtin_amdgcn_fence(__ATOMIC_ACQUIRE, "agent");
;             asm volatile("s_waitcnt vmcnt(0)" ::: "memory");
; __global__ void __launch_bounds__(NTHR, 2) fwd_megakernel(Args a) {
;     ...
;         const int j = layer >> 1, odd = layer & 1;
;         const int n1 = odd ? 4 : 3;
;         const int nstep = n1 + 3;
;         for (int s = 0; s < nstep; ++s) {
.LBB0_288:
	s_andn2_saveexec_b64 s[6:7], s[6:7]
	s_cbranch_execz .LBB0_57
	v_readlane_b32 s6, v250, 33
	v_readlane_b32 s7, v249, 1
	s_and_b32 s8, s6, 1
	s_add_i32 s8, s8, 3
	s_sub_i32 s7, s7, s8
	s_cmp_gt_u32 s7, 1
	s_cbranch_scc1 .Lmy_full_barrier
	v_mov_b32_e32 v3, 0x23e28
	ds_read_b32 v3, v3
	s_waitcnt lgkmcnt(0)
	v_readfirstlane_b32 s7, v3
	s_cmp_eq_u32 s7, 1
	s_cbranch_scc0 .Lmy_full_barrier
	v_mov_b32_e32 v0, s26
	v_add_co_u32_e32 v2, vcc, 0x2000, v0
	v_mov_b32_e32 v0, s2
	s_nop 0
	v_addc_co_u32_e32 v3, vcc, 0, v0, vcc
	s_waitcnt vmcnt(0) lgkmcnt(0)
	buffer_inv sc1
	flat_atomic_add v[2:3], v194 offset:1024
	s_waitcnt vmcnt(0) lgkmcnt(0)
	s_branch .LBB0_57
.Lmy_full_barrier:
	v_mov_b32_e32 v2, s4
	v_add_co_u32_e32 v2, vcc, 0x3000, v2
	v_mov_b32_e32 v3, s5
	buffer_wbl2 sc1
	s_waitcnt vmcnt(0)
	v_addc_co_u32_e32 v3, vcc, 0, v3, vcc
	flat_atomic_add v2, v[2:3], v194 offset:1024 sc0
	v_cvt_f32_u32_e32 v3, v0
	v_sub_u32_e32 v4, 0, v0
	s_add_u32 s6, s4, 0x3500
	s_addc_u32 s7, s5, 0
	v_rcp_iflag_f32_e32 v3, v3
	s_mov_b64 s[10:11], -1
	v_mul_f32_e32 v3, 0x4f7ffffe, v3
	v_cvt_u32_f32_e32 v3, v3
	v_mul_lo_u32 v4, v4, v3
	v_mul_hi_u32 v4, v3, v4
	v_add_u32_e32 v3, v3, v4
	s_waitcnt vmcnt(0) lgkmcnt(0)
	v_mul_hi_u32 v3, v2, v3
	v_mul_lo_u32 v4, v3, v0
	v_add_u32_e32 v5, 1, v2
	v_sub_u32_e32 v2, v2, v4
	v_add_u32_e32 v6, 1, v3
	v_sub_u32_e32 v4, v2, v0
	v_cmp_ge_u32_e32 vcc, v2, v0
	s_nop 1
	v_cndmask_b32_e32 v3, v3, v6, vcc
	v_cndmask_b32_e32 v2, v2, v4, vcc
	v_add_u32_e32 v4, 1, v3
	v_cmp_ge_u32_e32 vcc, v2, v0
	s_nop 1
	v_cndmask_b32_e32 v4, v3, v4, vcc
	v_mad_u64_u32 v[2:3], s[8:9], v0, v4, v[0:1]
	v_cmp_ne_u32_e32 vcc, v5, v2
	v_mov_b64_e32 v[2:3], s[6:7]
	s_and_saveexec_b64 s[8:9], vcc
	s_cbranch_execz .LBB0_301
	v_mov_b64_e32 v[2:3], s[6:7]
	flat_load_dword v0, v[2:3] sc1
	s_mov_b64 s[14:15], 0
	s_waitcnt vmcnt(0) lgkmcnt(0)
	v_cmp_eq_u32_e32 vcc, v0, v4
	s_and_saveexec_b64 s[12:13], vcc
	s_cbranch_execz .LBB0_300
	s_add_u32 s10, s4, 0x200
	s_addc_u32 s11, s5, 0
	s_mov_b32 s24, 1
	s_mov_b64 s[4:5], 0
	s_branch .LBB0_293
